# on top of v14: both halves run their MLA MFMA block at s_setprio 1 (partner softmax VALU yields), reset to 0 before softmax
# baseline (speedup 1.0000x reference)
.LBB0_867:
	s_setprio 1
	s_waitcnt lgkmcnt(5)
	v_mfma_f32_32x32x16_bf16 v[98:113], v[82:85], v[114:117], v[66:81]
	s_waitcnt lgkmcnt(3)
	v_mfma_f32_32x32x16_bf16 v[82:97], v[210:213], v[114:117], v[66:81]
	ds_read_b128 v[210:213], v205 offset:96
	ds_read_b128 v[230:233], v205 offset:12896
	v_mfma_f32_32x32x16_bf16 v[98:113], v[206:209], v[118:121], v[98:113]
	s_waitcnt lgkmcnt(3)
	v_mfma_f32_32x32x16_bf16 v[82:97], v[222:225], v[118:121], v[82:97]
	ds_read_b128 v[206:209], v205 offset:128
	ds_read_b128 v[222:225], v205 offset:12928
	v_mfma_f32_32x32x16_bf16 v[98:113], v[218:221], v[122:125], v[98:113]
	s_waitcnt lgkmcnt(4)
	v_mfma_f32_32x32x16_bf16 v[82:97], v[226:229], v[122:125], v[82:97]
	ds_read_b128 v[218:221], v205 offset:160
	ds_read_b128 v[226:229], v205 offset:12960
	s_waitcnt lgkmcnt(5)
	v_mfma_f32_32x32x16_bf16 v[98:113], v[210:213], v[126:129], v[98:113]
	s_waitcnt lgkmcnt(4)
	v_mfma_f32_32x32x16_bf16 v[82:97], v[230:233], v[126:129], v[82:97]
	ds_read_b128 v[210:213], v205 offset:192
	ds_read_b128 v[230:233], v205 offset:12992
	s_waitcnt lgkmcnt(5)
	v_mfma_f32_32x32x16_bf16 v[98:113], v[206:209], v[130:133], v[98:113]
	s_waitcnt lgkmcnt(4)
	v_mfma_f32_32x32x16_bf16 v[82:97], v[222:225], v[130:133], v[82:97]
	ds_read_b128 v[206:209], v205 offset:224
	ds_read_b128 v[222:225], v205 offset:13024
	s_waitcnt lgkmcnt(5)
	v_mfma_f32_32x32x16_bf16 v[98:113], v[218:221], v[134:137], v[98:113]
	s_waitcnt lgkmcnt(4)
	v_mfma_f32_32x32x16_bf16 v[82:97], v[226:229], v[134:137], v[82:97]
	ds_read_b128 v[218:221], v205 offset:256
	ds_read_b128 v[226:229], v205 offset:13056
	s_waitcnt lgkmcnt(5)
	v_mfma_f32_32x32x16_bf16 v[98:113], v[210:213], v[138:141], v[98:113]
	s_waitcnt lgkmcnt(4)
	v_mfma_f32_32x32x16_bf16 v[82:97], v[230:233], v[138:141], v[82:97]
	ds_read_b128 v[210:213], v205 offset:288
	ds_read_b128 v[230:233], v205 offset:13088
	ds_read_b64_tr_b16 v[234:235], v214 offset:51200
	ds_read_b64_tr_b16 v[236:237], v214 offset:53248
	s_waitcnt lgkmcnt(7)
	v_mfma_f32_32x32x16_bf16 v[98:113], v[206:209], v[142:145], v[98:113]
	s_waitcnt lgkmcnt(6)
	v_mfma_f32_32x32x16_bf16 v[82:97], v[222:225], v[142:145], v[82:97]
	ds_read_b128 v[206:209], v205 offset:320
	ds_read_b128 v[222:225], v205 offset:13120
	ds_read_b64_tr_b16 v[238:239], v214 offset:55296
	ds_read_b64_tr_b16 v[240:241], v214 offset:57344
	s_waitcnt lgkmcnt(9)
	v_mfma_f32_32x32x16_bf16 v[98:113], v[218:221], v[146:149], v[98:113]
	s_waitcnt lgkmcnt(8)
	v_mfma_f32_32x32x16_bf16 v[82:97], v[226:229], v[146:149], v[82:97]
	ds_read_b128 v[218:221], v205 offset:352
	ds_read_b128 v[226:229], v205 offset:13152
	ds_read_b64_tr_b16 v[242:243], v214 offset:59392
	ds_read_b64_tr_b16 v[244:245], v214 offset:61440
	s_waitcnt lgkmcnt(11)
	v_mfma_f32_32x32x16_bf16 v[98:113], v[210:213], v[154:157], v[98:113]
	s_waitcnt lgkmcnt(10)
	v_mfma_f32_32x32x16_bf16 v[82:97], v[230:233], v[154:157], v[82:97]
	ds_read_b64_tr_b16 v[210:211], v214 offset:63488
	ds_read_b64_tr_b16 v[212:213], v215 offset:14336
	s_waitcnt lgkmcnt(9)
	v_mfma_f32_32x32x16_bf16 v[98:113], v[206:209], v[150:153], v[98:113]
	s_waitcnt lgkmcnt(8)
	v_mfma_f32_32x32x16_bf16 v[82:97], v[222:225], v[150:153], v[82:97]
	ds_read_b64_tr_b16 v[206:207], v214 offset:51712
	ds_read_b64_tr_b16 v[208:209], v214 offset:53760
	s_waitcnt lgkmcnt(7)
	v_mfma_f32_32x32x16_bf16 v[98:113], v[218:221], v[158:161], v[98:113]
	s_waitcnt lgkmcnt(6)
	v_mfma_f32_32x32x16_bf16 v[82:97], v[226:229], v[158:161], v[82:97]
	ds_read_b64_tr_b16 v[218:219], v214 offset:55808
	ds_read_b64_tr_b16 v[220:221], v214 offset:57856
	v_mfma_f32_32x32x16_bf16 v[50:65], v[162:165], v[234:237], v[50:65]
	ds_read_b64_tr_b16 v[222:223], v214 offset:59904
	ds_read_b64_tr_b16 v[224:225], v214 offset:61952
	v_mfma_f32_32x32x16_bf16 v[50:65], v[166:169], v[238:241], v[50:65]
	ds_read_b64_tr_b16 v[226:227], v214 offset:64000
	ds_read_b64_tr_b16 v[228:229], v215 offset:14848
	s_waitcnt lgkmcnt(10)
	v_mfma_f32_32x32x16_bf16 v[50:65], v[170:173], v[242:245], v[50:65]
	ds_read_b64_tr_b16 v[230:231], v214 offset:52224
	ds_read_b64_tr_b16 v[232:233], v214 offset:54272
	s_waitcnt lgkmcnt(10)
	v_mfma_f32_32x32x16_bf16 v[50:65], v[174:177], v[210:213], v[50:65]
	ds_read_b64_tr_b16 v[210:211], v214 offset:56320
	ds_read_b64_tr_b16 v[212:213], v214 offset:58368
	s_waitcnt lgkmcnt(10)
	v_mfma_f32_32x32x16_bf16 v[34:49], v[162:165], v[206:209], v[34:49]
	ds_read_b64_tr_b16 v[206:207], v214 offset:60416
	ds_read_b64_tr_b16 v[208:209], v214 offset:62464
	s_waitcnt lgkmcnt(10)
	v_mfma_f32_32x32x16_bf16 v[34:49], v[166:169], v[218:221], v[34:49]
	ds_read_b64_tr_b16 v[218:219], v214 offset:64512
	ds_read_b64_tr_b16 v[220:221], v215 offset:15360
	s_waitcnt lgkmcnt(10)
	v_mfma_f32_32x32x16_bf16 v[34:49], v[170:173], v[222:225], v[34:49]
	ds_read_b64_tr_b16 v[222:223], v214 offset:52736
	ds_read_b64_tr_b16 v[224:225], v214 offset:54784
	s_waitcnt lgkmcnt(10)
	v_mfma_f32_32x32x16_bf16 v[34:49], v[174:177], v[226:229], v[34:49]
	ds_read_b64_tr_b16 v[226:227], v214 offset:56832
	ds_read_b64_tr_b16 v[228:229], v214 offset:58880
	s_waitcnt lgkmcnt(10)
	v_mfma_f32_32x32x16_bf16 v[18:33], v[162:165], v[230:233], v[18:33]
	ds_read_b64_tr_b16 v[230:231], v214 offset:60928
	ds_read_b64_tr_b16 v[232:233], v214 offset:62976
	s_waitcnt lgkmcnt(10)
	v_mfma_f32_32x32x16_bf16 v[18:33], v[166:169], v[210:213], v[18:33]
	ds_read_b64_tr_b16 v[210:211], v214 offset:65024
	ds_read_b64_tr_b16 v[212:213], v215 offset:15872
	s_waitcnt lgkmcnt(10)
	v_mfma_f32_32x32x16_bf16 v[18:33], v[170:173], v[206:209], v[18:33]
	s_waitcnt lgkmcnt(8)
	v_mfma_f32_32x32x16_bf16 v[18:33], v[174:177], v[218:221], v[18:33]
	s_waitcnt lgkmcnt(6)
	v_mfma_f32_32x32x16_bf16 v[2:17], v[162:165], v[222:225], v[2:17]
	s_waitcnt lgkmcnt(4)
	v_mfma_f32_32x32x16_bf16 v[2:17], v[166:169], v[226:229], v[2:17]
	s_waitcnt lgkmcnt(2)
	v_mfma_f32_32x32x16_bf16 v[2:17], v[170:173], v[230:233], v[2:17]
	s_waitcnt lgkmcnt(0)
	v_mfma_f32_32x32x16_bf16 v[2:17], v[174:177], v[210:213], v[2:17]
	s_setprio 0
	s_and_b64 vcc, exec, s[4:5]
	s_cbranch_vccnz .LBB0_872
	s_waitcnt vmcnt(0) lgkmcnt(0)
	s_barrier
	s_cmpk_gt_u32 s53, 0x7d
	s_cbranch_scc1 .LBB0_870
	s_add_u32 s0, s74, s8
	s_addc_u32 s1, s33, s9
	s_add_u32 s0, s0, 0x36020000
	s_addc_u32 s1, s1, 0
	s_add_i32 s55, s55, 0
	v_lshl_add_u64 v[162:163], v[182:183], 1, s[0:1]
	s_add_i32 s62, s55, s54
	s_mov_b32 m0, s62
	s_nop 0
	global_load_lds_dwordx4 v[162:163], off
	v_lshl_add_u64 v[162:163], v[184:185], 1, s[0:1]
	s_add_i32 s62, s55, s71
	s_mov_b32 m0, s62
	s_nop 0
	global_load_lds_dwordx4 v[162:163], off
	v_lshl_add_u64 v[162:163], v[186:187], 1, s[0:1]
	s_add_i32 s55, s55, s70
	s_mov_b32 m0, s55
	s_nop 0
	global_load_lds_dwordx4 v[162:163], off

.LBB0_2811:
	s_setprio 1
	s_waitcnt lgkmcnt(5)
	v_mfma_f32_32x32x16_bf16 v[98:113], v[82:85], v[114:117], v[66:81]
	s_waitcnt lgkmcnt(3)
	v_mfma_f32_32x32x16_bf16 v[82:97], v[210:213], v[114:117], v[66:81]
	ds_read_b128 v[210:213], v205 offset:96
	ds_read_b128 v[230:233], v205 offset:12896
	v_mfma_f32_32x32x16_bf16 v[98:113], v[206:209], v[118:121], v[98:113]
	s_waitcnt lgkmcnt(3)
	v_mfma_f32_32x32x16_bf16 v[82:97], v[222:225], v[118:121], v[82:97]
	ds_read_b128 v[206:209], v205 offset:128
	ds_read_b128 v[222:225], v205 offset:12928
	v_mfma_f32_32x32x16_bf16 v[98:113], v[218:221], v[122:125], v[98:113]
	s_waitcnt lgkmcnt(4)
	v_mfma_f32_32x32x16_bf16 v[82:97], v[226:229], v[122:125], v[82:97]
	ds_read_b128 v[218:221], v205 offset:160
	ds_read_b128 v[226:229], v205 offset:12960
	s_waitcnt lgkmcnt(5)
	v_mfma_f32_32x32x16_bf16 v[98:113], v[210:213], v[126:129], v[98:113]
	s_waitcnt lgkmcnt(4)
	v_mfma_f32_32x32x16_bf16 v[82:97], v[230:233], v[126:129], v[82:97]
	ds_read_b128 v[210:213], v205 offset:192
	ds_read_b128 v[230:233], v205 offset:12992
	s_waitcnt lgkmcnt(5)
	v_mfma_f32_32x32x16_bf16 v[98:113], v[206:209], v[130:133], v[98:113]
	s_waitcnt lgkmcnt(4)
	v_mfma_f32_32x32x16_bf16 v[82:97], v[222:225], v[130:133], v[82:97]
	ds_read_b128 v[206:209], v205 offset:224
	ds_read_b128 v[222:225], v205 offset:13024
	s_waitcnt lgkmcnt(5)
	v_mfma_f32_32x32x16_bf16 v[98:113], v[218:221], v[134:137], v[98:113]
	s_waitcnt lgkmcnt(4)
	v_mfma_f32_32x32x16_bf16 v[82:97], v[226:229], v[134:137], v[82:97]
	ds_read_b128 v[218:221], v205 offset:256
	ds_read_b128 v[226:229], v205 offset:13056
	s_waitcnt lgkmcnt(5)
	v_mfma_f32_32x32x16_bf16 v[98:113], v[210:213], v[138:141], v[98:113]
	s_waitcnt lgkmcnt(4)
	v_mfma_f32_32x32x16_bf16 v[82:97], v[230:233], v[138:141], v[82:97]
	ds_read_b128 v[210:213], v205 offset:288
	ds_read_b128 v[230:233], v205 offset:13088
	ds_read_b64_tr_b16 v[234:235], v214 offset:51200
	ds_read_b64_tr_b16 v[236:237], v214 offset:53248
	s_waitcnt lgkmcnt(7)
	v_mfma_f32_32x32x16_bf16 v[98:113], v[206:209], v[142:145], v[98:113]
	s_waitcnt lgkmcnt(6)
	v_mfma_f32_32x32x16_bf16 v[82:97], v[222:225], v[142:145], v[82:97]
	ds_read_b128 v[206:209], v205 offset:320
	ds_read_b128 v[222:225], v205 offset:13120
	ds_read_b64_tr_b16 v[238:239], v214 offset:55296
	ds_read_b64_tr_b16 v[240:241], v214 offset:57344
	s_waitcnt lgkmcnt(9)
	v_mfma_f32_32x32x16_bf16 v[98:113], v[218:221], v[146:149], v[98:113]
	s_waitcnt lgkmcnt(8)
	v_mfma_f32_32x32x16_bf16 v[82:97], v[226:229], v[146:149], v[82:97]
	ds_read_b128 v[218:221], v205 offset:352
	ds_read_b128 v[226:229], v205 offset:13152
	ds_read_b64_tr_b16 v[242:243], v214 offset:59392
	ds_read_b64_tr_b16 v[244:245], v214 offset:61440
	s_waitcnt lgkmcnt(11)
	v_mfma_f32_32x32x16_bf16 v[98:113], v[210:213], v[154:157], v[98:113]
	s_waitcnt lgkmcnt(10)
	v_mfma_f32_32x32x16_bf16 v[82:97], v[230:233], v[154:157], v[82:97]
	ds_read_b64_tr_b16 v[210:211], v214 offset:63488
	ds_read_b64_tr_b16 v[212:213], v215 offset:14336
	s_waitcnt lgkmcnt(9)
	v_mfma_f32_32x32x16_bf16 v[98:113], v[206:209], v[150:153], v[98:113]
	s_waitcnt lgkmcnt(8)
	v_mfma_f32_32x32x16_bf16 v[82:97], v[222:225], v[150:153], v[82:97]
	ds_read_b64_tr_b16 v[206:207], v214 offset:51712
	ds_read_b64_tr_b16 v[208:209], v214 offset:53760
	s_waitcnt lgkmcnt(7)
	v_mfma_f32_32x32x16_bf16 v[98:113], v[218:221], v[158:161], v[98:113]
	s_waitcnt lgkmcnt(6)
	v_mfma_f32_32x32x16_bf16 v[82:97], v[226:229], v[158:161], v[82:97]
	ds_read_b64_tr_b16 v[218:219], v214 offset:55808
	ds_read_b64_tr_b16 v[220:221], v214 offset:57856
	v_mfma_f32_32x32x16_bf16 v[50:65], v[162:165], v[234:237], v[50:65]
	ds_read_b64_tr_b16 v[222:223], v214 offset:59904
	ds_read_b64_tr_b16 v[224:225], v214 offset:61952
	v_mfma_f32_32x32x16_bf16 v[50:65], v[166:169], v[238:241], v[50:65]
	ds_read_b64_tr_b16 v[226:227], v214 offset:64000
	ds_read_b64_tr_b16 v[228:229], v215 offset:14848
	s_waitcnt lgkmcnt(10)
	v_mfma_f32_32x32x16_bf16 v[50:65], v[170:173], v[242:245], v[50:65]
	ds_read_b64_tr_b16 v[230:231], v214 offset:52224
	ds_read_b64_tr_b16 v[232:233], v214 offset:54272
	s_waitcnt lgkmcnt(10)
	v_mfma_f32_32x32x16_bf16 v[50:65], v[174:177], v[210:213], v[50:65]
	ds_read_b64_tr_b16 v[210:211], v214 offset:56320
	ds_read_b64_tr_b16 v[212:213], v214 offset:58368
	s_waitcnt lgkmcnt(10)
	v_mfma_f32_32x32x16_bf16 v[34:49], v[162:165], v[206:209], v[34:49]
	ds_read_b64_tr_b16 v[206:207], v214 offset:60416
	ds_read_b64_tr_b16 v[208:209], v214 offset:62464
	s_waitcnt lgkmcnt(10)
	v_mfma_f32_32x32x16_bf16 v[34:49], v[166:169], v[218:221], v[34:49]
	ds_read_b64_tr_b16 v[218:219], v214 offset:64512
	ds_read_b64_tr_b16 v[220:221], v215 offset:15360
	s_waitcnt lgkmcnt(10)
	v_mfma_f32_32x32x16_bf16 v[34:49], v[170:173], v[222:225], v[34:49]
	ds_read_b64_tr_b16 v[222:223], v214 offset:52736
	ds_read_b64_tr_b16 v[224:225], v214 offset:54784
	s_waitcnt lgkmcnt(10)
	v_mfma_f32_32x32x16_bf16 v[34:49], v[174:177], v[226:229], v[34:49]
	ds_read_b64_tr_b16 v[226:227], v214 offset:56832
	ds_read_b64_tr_b16 v[228:229], v214 offset:58880
	s_waitcnt lgkmcnt(10)
	v_mfma_f32_32x32x16_bf16 v[18:33], v[162:165], v[230:233], v[18:33]
	ds_read_b64_tr_b16 v[230:231], v214 offset:60928
	ds_read_b64_tr_b16 v[232:233], v214 offset:62976
	s_waitcnt lgkmcnt(10)
	v_mfma_f32_32x32x16_bf16 v[18:33], v[166:169], v[210:213], v[18:33]
	ds_read_b64_tr_b16 v[210:211], v214 offset:65024
	ds_read_b64_tr_b16 v[212:213], v215 offset:15872
	s_waitcnt lgkmcnt(10)
	v_mfma_f32_32x32x16_bf16 v[18:33], v[170:173], v[206:209], v[18:33]
	s_waitcnt lgkmcnt(8)
	v_mfma_f32_32x32x16_bf16 v[18:33], v[174:177], v[218:221], v[18:33]
	s_waitcnt lgkmcnt(6)
	v_mfma_f32_32x32x16_bf16 v[2:17], v[162:165], v[222:225], v[2:17]
	s_waitcnt lgkmcnt(4)
	v_mfma_f32_32x32x16_bf16 v[2:17], v[166:169], v[226:229], v[2:17]
	s_waitcnt lgkmcnt(2)
	v_mfma_f32_32x32x16_bf16 v[2:17], v[170:173], v[230:233], v[2:17]
	s_waitcnt lgkmcnt(0)
	v_mfma_f32_32x32x16_bf16 v[2:17], v[174:177], v[210:213], v[2:17]
	s_setprio 0
	s_and_b64 vcc, exec, s[4:5]
	s_cbranch_vccnz .LBB0_2816
	s_waitcnt vmcnt(0) lgkmcnt(0)
	s_barrier
	s_cmpk_gt_u32 s82, 0x7d
	s_cbranch_scc1 .LBB0_2814
	s_add_u32 s0, s33, s8
	s_addc_u32 s1, s78, s9
	s_add_u32 s0, s0, 0x36020000
	s_addc_u32 s1, s1, 0
	s_add_i32 s62, s86, 0
	v_lshl_add_u64 v[162:163], v[182:183], 1, s[0:1]
	s_add_i32 s63, s62, s70
	s_mov_b32 m0, s63
	s_nop 0
	global_load_lds_dwordx4 v[162:163], off
	v_lshl_add_u64 v[162:163], v[184:185], 1, s[0:1]
	s_add_i32 s63, s62, s71
	s_mov_b32 m0, s63
	s_nop 0
	global_load_lds_dwordx4 v[162:163], off
	v_lshl_add_u64 v[162:163], v[186:187], 1, s[0:1]
	s_add_i32 s62, s62, s83
	s_mov_b32 m0, s62
	s_nop 0
	global_load_lds_dwordx4 v[162:163], off
